# decode-shift kernel extended: the runtime division by the m-group height replaced by shifts also in the conv in-projection and out-projection unit decodes (qkv left as is)
# speedup vs baseline: 1.0181x; 1.0022x over previous
;     __host__ __device__ bool next(int i, Unit& u) const {
;         const long L = (long)i * G + c; if (L >= nwg) return false;
;         int wgid = (int)L; { const int q = nwg / NXCD, r = nwg % NXCD, xcd = wgid % NXCD, off = wgid / NXCD; wgid = (xcd < r ? xcd * (q + 1) : r * (q + 1) + (xcd - r) * q) + off; }
;         const int nig = WGM * nN, gid = wgid / nig, fm = gid * WGM, gsz = (nM - fm) < WGM ? (nM - fm) : WGM;
;         u.pm = fm + ((wgid % nig) % gsz); u.pn = (wgid % nig) / gsz; u.sw = 0; return true;
.LBB0_126:
	s_add_i32 s61, s61, 1
	s_mul_i32 s4, s61, s36
	s_mul_hi_u32 s5, s61, s28
	s_add_i32 s5, s5, s4
	s_mul_i32 s4, s61, s28
	s_add_u32 s42, s4, s2
	s_addc_u32 s43, s5, s33
	v_cmp_gt_i64_e32 vcc, s[42:43], v[168:169]
	v_cmp_lt_i64_e64 s[4:5], s[42:43], v[166:167]
	s_cbranch_vccnz .LBB0_128
	s_ashr_i32 s16, s42, 31
	s_lshr_b32 s16, s16, 29
	s_add_i32 s16, s42, s16
	s_ashr_i32 s17, s16, 3
	s_and_b32 s16, s16, -8
	s_sub_i32 s16, s42, s16
	s_cmp_lt_i32 s16, 0
	s_movk_i32 s18, 0xc1
	s_cselect_b32 s18, s18, 0xc0
	s_mul_i32 s16, s16, s18
	s_add_i32 s16, s16, s17
	s_mul_hi_i32 s17, s16, 0x2aaaaaab
	s_lshr_b32 s18, s17, 31
	s_ashr_i32 s17, s17, 4
	s_add_i32 s17, s17, s18
	s_lshl_b32 s18, s17, 3
	s_mulk_i32 s17, 0x60
	s_sub_i32 s17, s16, s17
	s_lshr_b32 s16, s17, 3
	s_lshl_b32 s19, s16, 3
	s_sub_i32 s17, s17, s19
	s_add_i32 s18, s18, s17

;     __host__ __device__ bool next(int i, Unit& u) const {
;     ...
;         int wgid = (int)L; { const int q = nwg / NXCD, r = nwg % NXCD, xcd = wgid % NXCD, off = wgid / NXCD; wgid = (xcd < r ? xcd * (q + 1) : r * (q + 1) + (xcd - r) * q) + off; }
;         const int nig = WGM * nN, gid = wgid / nig, fm = gid * WGM, gsz = (nM - fm) < WGM ? (nM - fm) : WGM;
;         u.pm = fm + ((wgid % nig) % gsz); u.pn = (wgid % nig) / gsz; u.sw = 0; return true;
.LBB0_377:
	s_ashr_i32 s6, s42, 3
	s_add_i32 s6, s47, s6
	s_ashr_i32 s7, s6, 31
	s_lshr_b32 s7, s7, 27
	s_add_i32 s7, s6, s7
	s_ashr_i32 s42, s7, 5
	s_lshl_b32 s42, s42, 3
	s_andn2_b32 s7, s7, 31
	s_sub_i32 s6, s6, s7
	s_lshr_b32 s71, s6, 3
	s_lshl_b32 s7, s71, 3
	s_sub_i32 s6, s6, s7
	s_add_i32 s72, s42, s6
